# v35 plus static s_setprio 1 for waves 4-7 during the prompt-attention loop
# baseline (speedup 1.0000x reference)
; DI float score_bound(const Args& a, int lane) {
;     const float* gq = (const float*)a.in[I_GQH]; const float* gk = (const float*)a.in[I_GKH];
;     float mq = fmaxf(fabsf(gq[lane]), (lane < 32) ? fabsf(gq[64 + lane]) : 0.f), mk = fmaxf(fabsf(gk[lane]), (lane < 32) ? fabsf(gk[64 + lane]) : 0.f);
; #pragma unroll
;     for (int o = 1; o < 64; o <<= 1) { mq = fmaxf(mq, __shfl_xor(mq, o)); mk = fmaxf(mk, __shfl_xor(mk, o)); }
;     return 96.f * QSCALE * mq * mk;
; DI void attn_prompt_unit(const Args& a, LAS unsigned char* lds, int b, int h, int qb, float cB, int tid, int lane, int wave) {
;     ...
;     const int NT = 4 * (qb + 1);
;     const int kr0 = tid / 12, kp0 = tid % 12, kr1 = (tid + 512) / 12, kp1 = (tid + 512) % 12; const bool k1 = tid < 256;
;     const bf16* kbase = KF + ((size_t)b * SEQ) * 768 + h * 96;
;     const bf16* vbase = KVR + ((size_t)b * SEQ + (tid >> 3)) * 1024 + h * 128 + 64 + (tid & 7) * 8;
;     u32x4 kst0, kst1 = {0u, 0u, 0u, 0u}, vst;
;     kst0 = *(const u32x4*)(kbase + (size_t)kr0 * 768 + kp0 * 8); if (k1) kst1 = *(const u32x4*)(kbase + (size_t)kr1 * 768 + kp1 * 8); vst = *(const u32x4*)(vbase);
.LBB0_830:
	s_or_b64 exec, exec, s[2:3]
	v_mbcnt_lo_u32_b32 v2, -1, 0
	v_mbcnt_hi_u32_b32 v2, -1, v2
	v_and_b32_e32 v6, 64, v2
	v_add_u32_e32 v6, 64, v6
	v_xor_b32_e32 v7, 1, v2
	v_cmp_lt_i32_e32 vcc, v7, v6
	s_waitcnt vmcnt(0)
	v_max_f32_e64 v1, |v1|, |v1|
	s_cmpk_lt_i32 s97, 0x100
	v_cndmask_b32_e32 v7, v2, v7, vcc
	v_lshlrev_b32_e32 v217, 2, v7
	v_xor_b32_e32 v7, 2, v2
	v_cmp_lt_i32_e32 vcc, v7, v6
	s_cselect_b64 s[4:5], -1, 0
	s_lshl_b32 s46, s86, 5
	v_cndmask_b32_e32 v7, v2, v7, vcc
	v_lshlrev_b32_e32 v216, 2, v7
	v_xor_b32_e32 v7, 4, v2
	v_cmp_lt_i32_e32 vcc, v7, v6
	s_add_u32 s74, s50, 0x3600000
	s_addc_u32 s75, s51, 0
	v_cndmask_b32_e32 v7, v2, v7, vcc
	v_lshlrev_b32_e32 v215, 2, v7
	v_xor_b32_e32 v7, 8, v2
	v_cmp_lt_i32_e32 vcc, v7, v6
	s_add_u32 s40, s50, 0x3680200
	v_lshlrev_b32_e32 v120, 2, v0
	v_cndmask_b32_e32 v7, v2, v7, vcc
	v_lshlrev_b32_e32 v214, 2, v7
	v_xor_b32_e32 v7, 16, v2
	v_cmp_lt_i32_e32 vcc, v7, v6
	s_addc_u32 s41, s51, 0
	v_bfe_u32 v222, v0, 2, 2
	v_cndmask_b32_e32 v7, v2, v7, vcc
	v_lshlrev_b32_e32 v141, 2, v7
	v_xor_b32_e32 v7, 32, v2
	v_cmp_lt_i32_e32 vcc, v7, v6
	v_and_b32_e32 v213, 16, v0
	s_mov_b32 s7, 0
	v_cndmask_b32_e32 v2, v2, v7, vcc
	v_lshlrev_b32_e32 v143, 2, v2
	v_max_f32_e32 v2, v4, v4
	v_max_f32_e32 v1, v1, v2
	v_max_f32_e32 v2, v3, v3
	v_max_f32_e64 v3, |v5|, |v5|
	ds_bpermute_b32 v4, v217, v1
	v_max_f32_e32 v2, v3, v2
	ds_bpermute_b32 v3, v217, v2
	v_lshrrev_b32_e32 v5, 5, v142
	v_lshlrev_b32_e32 v211, 3, v5
	s_waitcnt lgkmcnt(1)
	v_max_f32_e32 v4, v4, v4
	v_max_f32_e32 v1, v1, v4
	s_waitcnt lgkmcnt(0)
	v_max_f32_e32 v3, v3, v3
	ds_bpermute_b32 v4, v216, v1
	v_max_f32_e32 v2, v2, v3
	ds_bpermute_b32 v3, v216, v2
	v_lshlrev_b32_e32 v118, 2, v5
	s_movk_i32 s2, 0x100
	s_waitcnt lgkmcnt(1)
	v_max_f32_e32 v4, v4, v4
	v_max_f32_e32 v1, v1, v4
	s_waitcnt lgkmcnt(0)
	v_max_f32_e32 v3, v3, v3
	ds_bpermute_b32 v4, v215, v1
	v_max_f32_e32 v2, v2, v3
	ds_bpermute_b32 v3, v215, v2
	v_writelane_b32 v245, s4, 2
	s_cmpk_gt_i32 s97, 0xff
	s_waitcnt lgkmcnt(1)
	v_max_f32_e32 v4, v4, v4
	v_max_f32_e32 v1, v1, v4
	s_waitcnt lgkmcnt(0)
	v_max_f32_e32 v3, v3, v3
	ds_bpermute_b32 v4, v214, v1
	v_max_f32_e32 v2, v2, v3
	ds_bpermute_b32 v3, v214, v2
	v_and_b32_e32 v210, 31, v0
	v_mov_b32_e32 v127, 0
	s_waitcnt lgkmcnt(1)
	v_max_f32_e32 v4, v4, v4
	v_max_f32_e32 v1, v1, v4
	s_waitcnt lgkmcnt(0)
	v_max_f32_e32 v3, v3, v3
	ds_bpermute_b32 v4, v141, v1
	v_max_f32_e32 v3, v2, v3
	ds_bpermute_b32 v5, v141, v3
	v_lshlrev_b32_e32 v220, 3, v0
	v_or_b32_e32 v218, 32, v142
	s_waitcnt lgkmcnt(1)
	v_max_f32_e32 v2, v4, v4
	v_max_f32_e32 v2, v1, v2
	s_waitcnt lgkmcnt(0)
	v_max_f32_e32 v1, v5, v5
	v_max_f32_e32 v1, v3, v1
	ds_bpermute_b32 v4, v143, v2
	ds_bpermute_b32 v3, v143, v1
	v_and_b32_e32 v5, 12, v120
	v_or_b32_e32 v219, v118, v222
	v_lshlrev_b32_e32 v221, 1, v213
	v_lshlrev_b32_e32 v212, 1, v5
	v_writelane_b32 v245, s5, 3
	s_cbranch_scc1 .LBB0_861
	s_waitcnt lgkmcnt(1)
	v_max_f32_e32 v4, v4, v4
	v_max_f32_e32 v2, v2, v2
	s_movk_i32 s3, 0x1556
	v_or_b32_e32 v6, 0x200, v0
	v_max_f32_e32 v2, v2, v4
	s_waitcnt lgkmcnt(0)
	v_max_f32_e32 v3, v3, v3
	v_max_f32_e32 v1, v1, v1
	v_mul_u32_u24_sdwa v7, v6, s3 dst_sel:DWORD dst_unused:UNUSED_PAD src0_sel:WORD_0 src1_sel:DWORD
	v_mul_f32_e32 v2, 0xc1622ae0, v2
	v_max_f32_e32 v1, v1, v3
	v_mul_u32_u24_e32 v5, 0x1556, v0
	v_lshrrev_b32_e32 v21, 16, v7
	s_movk_i32 s4, 0xd0
	v_readlane_b32 s52, v245, 52
	v_mul_f32_e32 v2, v2, v1
	v_and_b32_e32 v1, 7, v0
	v_lshrrev_b32_e32 v19, 16, v5
	v_mul_lo_u16_e32 v7, 12, v21
	v_lshrrev_b32_e32 v128, 3, v0
	v_mad_u32_u24 v24, v21, s4, 0
	s_movk_i32 s4, 0xc0
	v_lshlrev_b32_e32 v126, 2, v211
	v_readlane_b32 s53, v245, 53
	v_lshlrev_b32_e32 v1, 4, v1
	v_mul_lo_u16_e32 v5, 12, v19
	v_sub_u16_e32 v6, v6, v7
	v_mad_u32_u24 v22, v219, s4, 0
	v_lshl_add_u64 v[144:145], s[52:53], 0, v[126:127]
	v_lshl_add_u64 v[146:147], s[74:75], 0, v[126:127]
	v_lshl_add_u64 v[148:149], s[40:41], 0, v[126:127]
	v_lshl_or_b32 v126, v128, 11, v1
	v_sub_u16_e32 v5, v0, v5
	s_movk_i32 s22, 0x600
	v_lshlrev_b32_e32 v138, 4, v6
	s_add_u32 s23, s50, 0x1aa00000
	v_add3_u32 v229, v22, v221, v212
	v_lshl_add_u64 v[22:23], s[50:51], 0, v[126:127]
	s_mov_b64 s[4:5], 0x16e20080
	v_mov_b32_e32 v139, v127
	v_lshlrev_b16_e32 v20, 3, v5
	s_addc_u32 s24, s51, 0
	v_lshl_add_u64 v[150:151], v[22:23], 0, s[4:5]
	v_mad_u64_u32 v[22:23], s[4:5], v21, s22, v[138:139]
	v_lshlrev_b32_e32 v136, 1, v20
	s_add_u32 s8, s50, 0x15400000
	v_lshl_add_u64 v[22:23], s[50:51], 0, v[22:23]
	s_mov_b64 s[4:5], 0x1aa18000
	v_mov_b32_e32 v137, v127
	v_and_b32_e32 v18, 56, v220
	v_mul_lo_u16_e32 v5, 0x68, v19
	s_addc_u32 s9, s51, 0
	v_lshl_add_u64 v[152:153], v[22:23], 0, s[4:5]
	v_mad_u64_u32 v[22:23], s[12:13], v19, s22, v[136:137]
	v_lshlrev_b32_e32 v134, 3, v6
	v_lshlrev_b32_e32 v223, 1, v5
	v_mul_u32_u24_e32 v5, 0xc0, v128
	v_lshlrev_b32_e32 v6, 1, v18
	s_add_u32 s10, s50, 0x1d600000
	v_lshl_add_u64 v[22:23], s[50:51], 0, v[22:23]
	v_cmp_gt_u32_e64 s[2:3], s2, v0
	v_mul_hi_u32_u24_e32 v131, 0x600, v19
	v_mul_u32_u24_e32 v130, 0x600, v19
	v_mul_u32_u24_e32 v132, 0x300, v21
	v_add3_u32 v224, 0, v223, v136
	v_mul_u32_u24_e32 v225, 0xd0, v21
	v_add3_u32 v226, 0, v5, v6
	v_mul_u32_u24_e32 v227, 0xd0, v210
	v_mul_u32_u24_e32 v228, 0xd0, v218
	s_addc_u32 s11, s51, 0
	v_mov_b32_e32 v3, v2
	v_mov_b32_e32 v4, v2
	v_mov_b32_e32 v5, v2
	v_mov_b32_e32 v6, v2
	v_mov_b32_e32 v7, v2
	v_mov_b32_e32 v8, v2
	v_mov_b32_e32 v9, v2
	v_mov_b32_e32 v10, v2
	v_mov_b32_e32 v11, v2
	v_mov_b32_e32 v12, v2
	v_mov_b32_e32 v13, v2
	v_mov_b32_e32 v14, v2
	v_mov_b32_e32 v15, v2
	v_mov_b32_e32 v16, v2
	v_mov_b32_e32 v17, v2
	v_lshl_add_u64 v[154:155], v[22:23], 0, s[4:5]
	v_lshlrev_b32_e32 v156, 1, v20
	v_lshlrev_b32_e32 v158, 1, v18
	v_mov_b32_e32 v230, 0x358637bd
	s_mov_b64 s[12:13], 0x20000
	s_mov_b64 s[14:15], 0x18000
	v_lshlrev_b32_e32 v160, 1, v118
	v_add_u32_e32 v231, v24, v138
	s_mov_b32 s25, s97
	s_mov_b32 s26, s97
	v_readlane_b32 s54, v245, 54
	v_readlane_b32 s55, v245, 55
	v_readlane_b32 s56, v245, 56
	v_readlane_b32 s57, v245, 57
	v_readlane_b32 s58, v245, 58
	v_readlane_b32 s59, v245, 59
	v_readlane_b32 s60, v245, 60
	v_readlane_b32 s61, v245, 61
	v_readlane_b32 s62, v245, 62
	v_readlane_b32 s63, v245, 63
	v_readlane_b32 s64, v244, 0
	v_readlane_b32 s65, v244, 1
	v_readlane_b32 s66, v244, 2
	v_readlane_b32 s67, v244, 3
	s_cmp_gt_u32 s86, 3
	s_cbranch_scc0 .Lpa_noprio
	s_setprio 1
.Lpa_noprio:
	s_branch .LBB0_833

; #define LAS __attribute__((address_space(3)))
; DI int crow(int r, int hi) { return (r & 3) + 8 * (r >> 2) + 4 * hi; }
; DI void gla_c_phase(const Args& a, LAS unsigned char* lds, int vcu, int G, int tid, int lane, int wave) {
;     LAS float* bt = (LAS float*)lds;
;     LAS bf16* QH = (LAS bf16*)(lds + 32768);
;     LAS bf16* KH = (LAS bf16*)(lds + 32768 + 17408);
;     LAS bf16* VH = (LAS bf16*)(lds + 32768 + 2 * 17408);
;     LAS bf16* SH = (LAS bf16*)(lds + 32768 + 2 * 17408 + 20480);
;     LAS float* RS = (LAS float*)(lds + 32768 + 2 * 17408 + 20480 + 40960);
;     LAS float* gas = RS + 256;
;     const float* wa2_ = (const float*)a.in[I_WA2]; const float* ba_ = (const float*)a.in[I_BA]; const bf16* Z = (const bf16*)(a.ws + WS_Z); const bf16* GSP = (const bf16*)(a.ws + WS_GSP); bf16* MIX = (bf16*)(a.ws + WS_MIX);
;     const float* go = (const float*)a.in[I_GGLAO];
;     const int r32 = lane & 31, h2 = lane >> 5, dvb = wave >> 1, tb = wave & 1;
;     float wcol[16], bias = 0.f; int hcur = -1;
; #pragma unroll
;     for (int r = 0; r < 16; ++r) wcol[r] = 0.f;
;     for (int u = vcu; u < 1024; u += G) {
;         const int b = u >> 7, h = (u >> 5) & 3, c = u & 31, row0 = b * SEQ + c * 64;
;     ...
;             if (sb == tb) {
; #pragma unroll
;                 for (int r = 0; r < 16; ++r) if (crow(r, h2) > r32) p[r] = 0.f; }
.LBB0_861:
	s_setprio 0
	s_movk_i32 s2, 0xff
	s_cmpk_gt_i32 s97, 0x3ff
	v_cmp_lt_u32_e64 s[2:3], s2, v0
	v_or_b32_e32 v85, v211, v222
	s_cbranch_scc1 .LBB0_883
	v_and_b32_e32 v2, 0x7f, v0
	v_lshlrev_b32_e32 v104, 2, v2
	v_and_b32_e32 v2, 0x78, v220
	s_add_u32 s94, s50, 0xcc00000
	v_mov_b32_e32 v11, 0
	v_lshlrev_b32_e32 v10, 1, v2
	s_addc_u32 s95, s51, 0
	s_bfe_u32 s10, s80, 0x10006
	v_lshl_add_u32 v17, v2, 2, 0
	s_waitcnt lgkmcnt(0)
	v_lshl_add_u64 v[2:3], s[50:51], 0, v[10:11]
	s_mov_b64 s[8:9], 0x30400000
	s_lshr_b32 s11, s80, 7
	v_lshl_add_u64 v[82:83], v[2:3], 0, s[8:9]
	v_lshl_add_u32 v19, v211, 1, 0
	v_lshl_or_b32 v84, s10, 5, v210
	s_movk_i32 s9, 0x110
	s_add_i32 s8, 0, 0x15800
	v_mad_u32_u24 v108, v84, s9, v19
	s_lshl_b32 s9, s11, 6
	s_add_i32 s12, 0, 0x10800
	v_add_u32_e32 v107, s8, v10
	s_add_i32 s8, s8, s9
	v_add_u32_e32 v106, s12, v10
	s_add_i32 s12, s12, s9
	v_add3_u32 v23, s8, v221, v212
	s_lshl_b32 s8, s11, 8
	s_add_i32 s9, 0, 0x1f800
	v_add3_u32 v21, s12, v221, v212
	s_add_i32 s8, s9, s8
	s_lshl_b32 s12, s10, 7
	s_add_i32 s8, s8, s12
	v_readlane_b32 s12, v245, 52
	v_or_b32_e32 v2, 0x1e00, v120
	v_or_b32_e32 v1, 8, v118
	v_lshl_or_b32 v18, s11, 5, v118
	v_readlane_b32 s18, v245, 58
	v_readlane_b32 s19, v245, 59
	v_add_u32_e32 v111, 0, v2
	v_or_b32_e32 v2, 0x3e00, v120
	v_writelane_b32 v244, s40, 11
	v_lshl_add_u64 v[80:81], s[94:95], 0, v[10:11]
	v_sub_u32_e32 v8, v17, v10
	v_lshlrev_b32_e32 v10, 2, v18
	v_readlane_b32 s20, v245, 60
	v_readlane_b32 s21, v245, 61
	v_add_u32_e32 v112, 0, v2
	v_or_b32_e32 v2, 0x5e00, v120
	v_lshrrev_b32_e32 v114, 4, v0
	v_cmp_gt_u32_e64 s[18:19], v1, v210
	v_or_b32_e32 v1, 9, v118
	v_writelane_b32 v244, s41, 12
	v_readlane_b32 s22, v245, 62
	v_readlane_b32 s23, v245, 63
	v_lshl_add_u64 v[86:87], s[20:21], 0, v[10:11]
	v_add_u32_e32 v113, 0, v2
	v_mul_u32_u24_e32 v2, 0x88, v114
	v_cmp_gt_u32_e64 s[20:21], v1, v210
	v_or_b32_e32 v1, 10, v118
	v_readlane_b32 s24, v244, 0
	v_readlane_b32 s25, v244, 1
	v_lshl_add_u32 v115, v2, 1, v8
	v_or_b32_e32 v2, 0x200, v0
	v_cmp_gt_u32_e64 s[22:23], v1, v210
	v_or_b32_e32 v1, 11, v118
	v_lshrrev_b32_e32 v117, 4, v2
	v_cmp_gt_u32_e64 s[24:25], v1, v210
	v_or_b32_e32 v1, 17, v118
	v_mul_u32_u24_e32 v2, 0x88, v117
	v_cmp_gt_u32_e64 s[28:29], v1, v210
	v_or_b32_e32 v1, 18, v118
	v_lshl_add_u32 v119, v2, 1, v8
	v_or_b32_e32 v2, 0x600, v0
	v_cmp_gt_u32_e64 s[30:31], v1, v210
	v_or_b32_e32 v1, 19, v118
	v_lshrrev_b32_e32 v2, 4, v2
	s_and_b32 s11, 64, s80
	v_cmp_gt_u32_e64 s[34:35], v1, v210
	v_or_b32_e32 v1, 25, v118
	v_lshlrev_b32_e32 v15, 5, v0
	v_lshrrev_b32_e32 v6, 7, v0
	v_readlane_b32 s14, v245, 54
	v_readlane_b32 s15, v245, 55
	v_lshlrev_b32_e32 v10, 7, v114
	v_lshlrev_b32_e32 v24, 7, v2
	v_mul_u32_u24_e32 v27, 0x140, v2
	s_cmp_eq_u32 s10, 0
	v_or_b32_e32 v2, 2, v118
	v_cmp_gt_u32_e64 s[38:39], v1, v210
	v_or_b32_e32 v1, 26, v118
	v_or_b32_e32 v4, 16, v118
	v_or_b32_e32 v5, 24, v118
	s_movk_i32 s4, 0x80
	s_movk_i32 s6, 0x7f
	v_and_b32_e32 v16, 8, v220
	v_lshlrev_b32_e32 v7, 13, v6
	s_mov_b32 s52, s97
	v_lshl_add_u32 v109, v142, 2, s8
	v_readlane_b32 s13, v245, 53
	v_readlane_b32 s16, v245, 56
	v_readlane_b32 s17, v245, 57
	v_readlane_b32 s26, v244, 2
	v_readlane_b32 s27, v244, 3
	s_movk_i32 s8, 0x17f
	v_lshlrev_b32_e32 v25, 9, v114
	v_lshlrev_b32_e32 v26, 9, v117
	v_lshlrev_b32_e32 v20, 7, v117
	v_or_b32_e32 v22, 0x2000, v10
	v_mul_u32_u24_e32 v28, 0x110, v210
	s_cselect_b64 s[68:69], -1, 0
	s_cmp_lg_u32 s11, 0
	v_cmp_gt_u32_e64 s[14:15], v2, v210
	v_or_b32_e32 v2, 3, v118
	v_cmp_gt_u32_e64 s[40:41], v1, v210
	v_or_b32_e32 v1, 27, v118
	v_mul_u32_u24_e32 v29, 0x140, v219
	v_mul_u32_u24_e32 v30, 0x110, v218
	v_mul_u32_u24_e32 v31, 0x140, v85
	v_add_u32_e32 v15, 0, v15
	s_mov_b32 s78, s86
	v_cmp_gt_u32_e64 s[4:5], s4, v0
	v_cmp_lt_u32_e64 s[6:7], s6, v0
	v_lshrrev_b32_e32 v9, 1, v0
	s_mov_b32 s97, 0
	v_add3_u32 v105, 0, v7, v104
	v_lshl_add_u32 v110, v84, 2, s9
	v_cmp_lt_u32_e64 s[8:9], s8, v0
	v_mul_u32_u24_e32 v116, 0x140, v114
	v_mul_u32_u24_e32 v121, 0x140, v117
	s_cselect_b64 s[86:87], -1, 0
	v_cmp_gt_u32_e64 s[10:11], v118, v210
	v_cmp_lt_u32_e64 s[12:13], v118, v210
	v_cmp_gt_u32_e64 s[16:17], v2, v210
	v_cmp_gt_u32_e64 s[26:27], v4, v210
	v_cmp_gt_u32_e64 s[36:37], v5, v210
	v_cmp_gt_u32_e64 s[42:43], v1, v210
	v_or_b32_e32 v126, v7, v104
	v_lshlrev_b32_e32 v127, 10, v6
	v_mov_b32_e32 v2, v11
	v_mov_b32_e32 v1, v11
	v_mov_b32_e32 v4, v11
	v_mov_b32_e32 v3, v11
	v_mov_b32_e32 v6, v11
	v_mov_b32_e32 v5, v11
	v_mov_b32_e32 v8, v11
	v_mov_b32_e32 v7, v11
	v_mov_b32_e32 v100, v11
	v_mov_b32_e32 v101, v11
	v_mov_b32_e32 v102, v11
	v_mov_b32_e32 v103, v11
	v_mov_b32_e32 v12, v11
	v_mov_b32_e32 v13, v11
	v_mov_b32_e32 v14, v11
	s_mov_b32 s45, -1
	s_movk_i32 s47, 0x1600
	v_lshlrev_b32_e32 v88, 1, v16
	v_add_u32_e32 v128, 0x1fc00, v15
	s_mov_b32 s77, 0xbfb8aa3b
	s_mov_b32 s70, 0x800000
	s_mov_b32 s71, 0x3f317217
	s_mov_b32 s44, 0x7f800000
	v_add_u32_e32 v129, v17, v25
	s_mov_b32 s76, 0x3db504f3
	v_add_u32_e32 v130, v17, v26
	v_lshlrev_b32_e32 v10, 1, v10
	v_lshlrev_b32_e32 v90, 1, v20
	v_lshlrev_b32_e32 v92, 1, v22
	v_lshlrev_b32_e32 v94, 1, v24
	v_add_u32_e32 v131, v107, v27
	v_add_u32_e32 v132, v19, v28
	v_add_u32_e32 v133, v19, v30
	v_add_u32_e32 v134, v23, v31
	v_mov_b32_e32 v135, 0x358637bd
	v_lshlrev_b32_e32 v96, 1, v18
	v_mov_b32_e32 v136, 0x41b17218
	v_add_u32_e32 v137, v21, v29
	v_mov_b32_e32 v98, v11
	s_mov_b32 s84, s52
	v_mov_b32_e32 v15, v11
	s_branch .LBB0_864
